# NA attention: 32 serialized masked bias reads replaced by 3 batched LDS read groups + cndmask
# speedup vs baseline: 1.0011x; 1.0011x over previous
; __device__ __forceinline__ void na_unit(const bf16_t* __restrict__ QKV, bf16_t* __restrict__ O, const float* __restrict__ rpb, int tok0, int rows, int g4, int h, char* lds) {
;     ...
;       f32x16 p0 = {}, p1 = {};
; #pragma unroll
;       for (int d0 = 0; d0 < 4; ++d0) { const int cb = (d0 * 16 + hi * 8) * 2;
;         const bf16x8 b0 = *reinterpret_cast<const bf16x8*>(Ks + r32 * 144 + cb), b1 = *reinterpret_cast<const bf16x8*>(Ks + (32 + r32) * 144 + cb);
;         p0 = __builtin_amdgcn_mfma_f32_32x32x16_bf16(b0, qf[d0], p0, 0, 0, 0); p1 = __builtin_amdgcn_mfma_f32_32x32x16_bf16(b1, qf[d0], p1, 0, 0, 0); }
;       const float* Tr = T + (kr - qr + 7) * 128 + tb;
; #pragma unroll
;       for (int r = 0; r < 16; ++r) { const int ko = (r & 3) + 8 * (r >> 2), kc = ko + 4 * hi;
;         const bool v0 = (kc >= c0) && (kc <= c0 + 15), v1 = (kc + 32 >= c0) && (kc + 32 <= c0 + 15);
;         p0[r] = v0 ? fmaf(p0[r], 0.125f, Tr[ko]) : -1e30f; p1[r] = v1 ? fmaf(p1[r], 0.125f, Tr[ko + 32]) : -1e30f; }
.LBB0_388:
	s_and_b32 s13, s20, 1
	s_add_i32 s24, s15, s20
	s_cmp_lt_u32 s24, s23
	s_cselect_b64 vcc, -1, 0
	s_cmp_gt_u32 s24, s95
	s_cselect_b64 s[24:25], -1, 0
	s_or_b64 s[24:25], vcc, s[24:25]
	s_and_b64 vcc, exec, s[24:25]
	s_cbranch_vccnz .LBB0_458
	s_mul_i32 s24, s13, 0x2400
	v_add_u32_e32 v0, s24, v117
	ds_read_b128 v[2:5], v0 offset:32768
	s_waitcnt vmcnt(3) lgkmcnt(0)
	v_mfma_f32_32x32x16_bf16 v[66:81], v[2:5], v[86:89], 0
	ds_read_b128 v[2:5], v0 offset:37376
	s_waitcnt lgkmcnt(0)
	v_mfma_f32_32x32x16_bf16 v[50:65], v[2:5], v[86:89], 0
	ds_read_b128 v[2:5], v0 offset:32800
	s_waitcnt vmcnt(2) lgkmcnt(0)
	v_mfma_f32_32x32x16_bf16 v[66:81], v[2:5], v[94:97], v[66:81]
	ds_read_b128 v[2:5], v0 offset:37408
	s_waitcnt lgkmcnt(0)
	v_mfma_f32_32x32x16_bf16 v[50:65], v[2:5], v[94:97], v[50:65]
	ds_read_b128 v[2:5], v0 offset:32832
	s_waitcnt vmcnt(1) lgkmcnt(0)
	v_mfma_f32_32x32x16_bf16 v[66:81], v[2:5], v[98:101], v[66:81]
	ds_read_b128 v[2:5], v0 offset:37440
	s_waitcnt lgkmcnt(0)
	v_mfma_f32_32x32x16_bf16 v[50:65], v[2:5], v[98:101], v[50:65]
	ds_read_b128 v[2:5], v0 offset:32864
	s_waitcnt vmcnt(0) lgkmcnt(0)
	v_mfma_f32_32x32x16_bf16 v[66:81], v[2:5], v[102:105], v[66:81]
	ds_read_b128 v[4:7], v0 offset:37472
	v_mov_b32_e32 v0, 0xf149f2ca
	v_mov_b32_e32 v2, 0xf149f2ca
	s_waitcnt lgkmcnt(0)
	v_mfma_f32_32x32x16_bf16 v[50:65], v[4:7], v[102:105], v[50:65]
	ds_read_b32 v120, v116 offset:0
	ds_read_b32 v121, v116 offset:128
	ds_read_b32 v122, v116 offset:4
	ds_read_b32 v123, v116 offset:132
	ds_read_b32 v124, v116 offset:8
	ds_read_b32 v125, v116 offset:136
	ds_read_b32 v126, v116 offset:12
	ds_read_b32 v127, v116 offset:140
	ds_read_b32 v128, v116 offset:32
	ds_read_b32 v129, v116 offset:160
	ds_read_b32 v130, v116 offset:36
	ds_read_b32 v131, v116 offset:164
	v_mov_b32_e32 v152, 0xf149f2ca
	s_waitcnt lgkmcnt(0)
	ds_read_b32 v132, v116 offset:40
	ds_read_b32 v133, v116 offset:168
	ds_read_b32 v134, v116 offset:44
	ds_read_b32 v135, v116 offset:172
	ds_read_b32 v136, v116 offset:64
	ds_read_b32 v137, v116 offset:192
	ds_read_b32 v138, v116 offset:68
	ds_read_b32 v139, v116 offset:196
	ds_read_b32 v140, v116 offset:72
	ds_read_b32 v141, v116 offset:200
	ds_read_b32 v142, v116 offset:76
	ds_read_b32 v143, v116 offset:204
	v_fmac_f32_e32 v120, 0x3e000000, v66
	v_fmac_f32_e32 v121, 0x3e000000, v50
	v_fmac_f32_e32 v122, 0x3e000000, v67
	v_fmac_f32_e32 v123, 0x3e000000, v51
	v_fmac_f32_e32 v124, 0x3e000000, v68
	v_fmac_f32_e32 v125, 0x3e000000, v52
	v_fmac_f32_e32 v126, 0x3e000000, v69
	v_fmac_f32_e32 v127, 0x3e000000, v53
	v_fmac_f32_e32 v128, 0x3e000000, v70
	v_fmac_f32_e32 v129, 0x3e000000, v54
	v_fmac_f32_e32 v130, 0x3e000000, v71
	v_fmac_f32_e32 v131, 0x3e000000, v55
	s_waitcnt lgkmcnt(0)
	ds_read_b32 v144, v116 offset:96
	ds_read_b32 v145, v116 offset:224
	ds_read_b32 v146, v116 offset:100
	ds_read_b32 v147, v116 offset:228
	ds_read_b32 v148, v116 offset:104
	ds_read_b32 v149, v116 offset:232
	ds_read_b32 v150, v116 offset:108
	ds_read_b32 v151, v116 offset:236
	v_fmac_f32_e32 v132, 0x3e000000, v72
	v_fmac_f32_e32 v133, 0x3e000000, v56
	v_fmac_f32_e32 v134, 0x3e000000, v73
	v_fmac_f32_e32 v135, 0x3e000000, v57
	v_fmac_f32_e32 v136, 0x3e000000, v74
	v_fmac_f32_e32 v137, 0x3e000000, v58
	v_fmac_f32_e32 v138, 0x3e000000, v75
	v_fmac_f32_e32 v139, 0x3e000000, v59
	v_fmac_f32_e32 v140, 0x3e000000, v76
	v_fmac_f32_e32 v141, 0x3e000000, v60
	v_fmac_f32_e32 v142, 0x3e000000, v77
	v_fmac_f32_e32 v143, 0x3e000000, v61
	s_waitcnt lgkmcnt(0)
	v_fmac_f32_e32 v144, 0x3e000000, v78
	v_fmac_f32_e32 v145, 0x3e000000, v62
	v_fmac_f32_e32 v146, 0x3e000000, v79
	v_fmac_f32_e32 v147, 0x3e000000, v63
	v_fmac_f32_e32 v148, 0x3e000000, v80
	v_fmac_f32_e32 v149, 0x3e000000, v64
	v_fmac_f32_e32 v150, 0x3e000000, v81
	v_fmac_f32_e32 v151, 0x3e000000, v65
	v_cndmask_b32_e64 v2, v152, v120, s[40:41]
	v_cndmask_b32_e64 v0, v152, v121, s[26:27]
	v_cndmask_b32_e64 v4, v152, v122, s[42:43]
	v_cndmask_b32_e64 v3, v152, v123, s[34:35]
	v_cndmask_b32_e64 v6, v152, v124, s[44:45]
	v_cndmask_b32_e64 v5, v152, v125, s[78:79]
	v_cndmask_b32_e64 v8, v152, v126, s[46:47]
	v_cndmask_b32_e64 v7, v152, v127, s[80:81]
	v_cndmask_b32_e64 v10, v152, v128, s[48:49]
	v_cndmask_b32_e64 v9, v152, v129, s[82:83]
	v_cndmask_b32_e64 v12, v152, v130, s[50:51]
	v_cndmask_b32_e64 v11, v152, v131, s[84:85]
	v_cndmask_b32_e64 v14, v152, v132, s[52:53]
	v_cndmask_b32_e64 v13, v152, v133, s[86:87]
	v_cndmask_b32_e64 v50, v152, v134, s[54:55]
	v_cndmask_b32_e64 v15, v152, v135, s[88:89]
	v_cndmask_b32_e64 v52, v152, v136, s[90:91]
	v_cndmask_b32_e64 v51, v152, v137, s[56:57]
	v_cndmask_b32_e64 v55, v152, v138, s[16:17]
	v_cndmask_b32_e64 v53, v152, v139, s[58:59]
	v_cndmask_b32_e64 v57, v152, v140, s[96:97]
	v_cndmask_b32_e64 v56, v152, v141, s[60:61]
	v_cndmask_b32_e64 v59, v152, v142, s[4:5]
	v_cndmask_b32_e64 v58, v152, v143, s[62:63]
	v_cndmask_b32_e64 v61, v152, v144, s[18:19]
	v_cndmask_b32_e64 v60, v152, v145, s[64:65]
	v_cndmask_b32_e64 v66, v152, v146, s[2:3]
	v_cndmask_b32_e64 v62, v152, v147, s[66:67]
	v_cndmask_b32_e64 v67, v152, v148, s[28:29]
	v_cndmask_b32_e64 v63, v152, v149, s[68:69]
	v_cndmask_b32_e64 v68, v152, v150, s[72:73]
	v_cndmask_b32_e64 v64, v152, v151, s[70:71]
	v_max_f32_e32 v54, v4, v4
	v_max_f32_e32 v65, v2, v2
	v_max_f32_e32 v54, v65, v54
	v_max3_f32 v54, v54, v6, v8
	v_max3_f32 v54, v54, v10, v12
	v_max3_f32 v54, v54, v14, v50
	v_max3_f32 v54, v54, v52, v55
	v_max3_f32 v54, v54, v57, v59
	v_max3_f32 v54, v54, v61, v66
	v_max3_f32 v54, v54, v67, v68
	v_max3_f32 v54, v54, v0, v3
	v_max3_f32 v54, v54, v5, v7
; __device__ __forceinline__ int crow(int r, int hi) { return (r & 3) + 8 * (r >> 2) + 4 * hi; }
; template <int DQK> __device__ __forceinline__ void partialSM(f32x16& p0, f32x16& p1, float& m_reg, float& mn, float& alpha) {
;   constexpr float SCALE = (DQK == 192) ? 0.07216878364870322f : (DQK == 64 ? 1.0f : 0.08838834764831845f);
;   constexpr float C = SCALE * 1.4426950408889634f;
;   float pmax = p0[0];
; #pragma unroll
;   for (int r = 1; r < 16; ++r) pmax = fmaxf(pmax, p0[r]);
; #pragma unroll
;   for (int r = 0; r < 16; ++r) pmax = fmaxf(pmax, p1[r]);
;   { auto rr = __builtin_amdgcn_permlane32_swap(__float_as_uint(pmax), __float_as_uint(pmax), false, false);
;     pmax = fmaxf(__uint_as_float(rr[0]), __uint_as_float(rr[1])); }
;   if (__builtin_expect(__all(pmax - m_reg <= THR / SCALE), 1)) { mn = m_reg; alpha = 1.f; }
;   else { mn = fmaxf(m_reg, pmax); alpha = __builtin_amdgcn_exp2f((m_reg - mn) * C); m_reg = mn; }
;   float mnC = -mn * C;
; #pragma unroll
;   for (int r = 0; r < 16; ++r) p0[r] = fmaf(p0[r], C, mnC);
; #pragma unroll
;   for (int r = 0; r < 16; ++r) p1[r] = fmaf(p1[r], C, mnC);
; #pragma unroll
;   for (int r = 0; r < 16; ++r) p0[r] = __builtin_amdgcn_exp2f(p0[r]);
; }
; __device__ __forceinline__ void finishSM(f32x16& p0, f32x16& p1, float alpha, float& l_reg, bf16x8& pa0, bf16x8& pa1, bf16x8& pa2, bf16x8& pa3) {
; #pragma unroll
;   for (int r = 0; r < 16; ++r) p1[r] = __builtin_amdgcn_exp2f(p1[r]);
;   float ps = 0;
; #pragma unroll
;   for (int r = 0; r < 16; ++r) ps += p0[r];
; #pragma unroll
;   for (int r = 0; r < 16; ++r) ps += p1[r];
;   { auto rr = __builtin_amdgcn_permlane32_swap(__float_as_uint(ps), __float_as_uint(ps), false, false);
;     ps = __uint_as_float(rr[0]) + __uint_as_float(rr[1]); }
;   l_reg = l_reg * alpha + ps;
;     ...
;   PK4(p0, 0, pa0); PK4(p0, 8, pa1); PK4(p1, 0, pa2); PK4(p1, 8, pa3);
;     ...
; }
; __device__ __forceinline__ void na_unit(const bf16_t* __restrict__ QKV, bf16_t* __restrict__ O, const float* __restrict__ rpb, int tok0, int rows, int g4, int h, char* lds) {
;     ...
;       if (__any(al < 1.f)) { if (hi == 0) al_l[r32] = al; asm volatile("s_waitcnt lgkmcnt(0)" ::: "memory");
; #pragma unroll
;         for (int d = 0; d < 2; ++d)
; #pragma unroll
;           for (int r = 0; r < 16; ++r) o[d][r] *= al_l[crow(r, hi)]; }
	v_max3_f32 v54, v54, v9, v11
	v_max3_f32 v54, v54, v13, v15
	v_max3_f32 v54, v54, v51, v53
	v_max3_f32 v54, v54, v56, v58
	v_max3_f32 v54, v54, v60, v62
	v_max3_f32 v54, v54, v63, v64
	v_mov_b32_e32 v65, v54
	s_nop 1
	v_permlane32_swap_b32_e32 v54, v65
	v_max_f32_e32 v65, v65, v65
	v_max_f32_e32 v54, v54, v54
	v_max_f32_e32 v54, v54, v65
	v_sub_f32_e32 v65, v54, v118
	s_mov_b32 s24, 0x41000000
	v_cmp_ge_f32_e32 vcc, s24, v65
	v_max_f32_e32 v69, v118, v118
	s_cmp_eq_u64 vcc, exec
	v_max_f32_e32 v69, v69, v54
	s_cselect_b64 vcc, -1, 0
	v_sub_f32_e32 v54, v118, v69
	v_cndmask_b32_e32 v118, v69, v118, vcc
	v_mul_f32_e32 v65, 0xbfb8aa3b, v118
	v_fmamk_f32 v2, v2, 0x3fb8aa3b, v65
	v_fmamk_f32 v4, v4, 0x3fb8aa3b, v65
	v_exp_f32_e32 v2, v2
	v_fmamk_f32 v6, v6, 0x3fb8aa3b, v65
	v_exp_f32_e32 v4, v4
	v_fmamk_f32 v8, v8, 0x3fb8aa3b, v65
	v_exp_f32_e32 v6, v6
	v_fmamk_f32 v10, v10, 0x3fb8aa3b, v65
	v_fmamk_f32 v0, v0, 0x3fb8aa3b, v65
	v_exp_f32_e32 v8, v8
	v_fmamk_f32 v12, v12, 0x3fb8aa3b, v65
	v_exp_f32_e32 v10, v10
	v_exp_f32_e32 v69, v0
	v_add_f32_e32 v0, 0, v2
	v_fmamk_f32 v14, v14, 0x3fb8aa3b, v65
	v_exp_f32_e32 v12, v12
	v_add_f32_e32 v0, v4, v0
	v_fmamk_f32 v50, v50, 0x3fb8aa3b, v65
	v_fmamk_f32 v52, v52, 0x3fb8aa3b, v65
	v_fmamk_f32 v55, v55, 0x3fb8aa3b, v65
	v_fmamk_f32 v57, v57, 0x3fb8aa3b, v65
	v_fmamk_f32 v59, v59, 0x3fb8aa3b, v65
	v_fmamk_f32 v61, v61, 0x3fb8aa3b, v65
	v_fmamk_f32 v66, v66, 0x3fb8aa3b, v65
	v_fmamk_f32 v67, v67, 0x3fb8aa3b, v65
	v_fmamk_f32 v68, v68, 0x3fb8aa3b, v65
	v_fmamk_f32 v3, v3, 0x3fb8aa3b, v65
	v_fmamk_f32 v5, v5, 0x3fb8aa3b, v65
	v_fmamk_f32 v7, v7, 0x3fb8aa3b, v65
	v_fmamk_f32 v9, v9, 0x3fb8aa3b, v65
	v_fmamk_f32 v11, v11, 0x3fb8aa3b, v65
	v_fmamk_f32 v13, v13, 0x3fb8aa3b, v65
	v_fmamk_f32 v15, v15, 0x3fb8aa3b, v65
	v_fmamk_f32 v51, v51, 0x3fb8aa3b, v65
	v_fmamk_f32 v53, v53, 0x3fb8aa3b, v65
	v_fmamk_f32 v56, v56, 0x3fb8aa3b, v65
	v_fmamk_f32 v58, v58, 0x3fb8aa3b, v65
	v_fmamk_f32 v60, v60, 0x3fb8aa3b, v65
	v_fmamk_f32 v62, v62, 0x3fb8aa3b, v65
	v_fmamk_f32 v63, v63, 0x3fb8aa3b, v65
	v_fmac_f32_e32 v65, 0x3fb8aa3b, v64
	v_exp_f32_e32 v64, v14
	v_add_f32_e32 v0, v6, v0
	v_exp_f32_e32 v50, v50
	v_add_f32_e32 v0, v8, v0
	v_exp_f32_e32 v52, v52
	v_add_f32_e32 v0, v10, v0
	v_exp_f32_e32 v55, v55
	v_add_f32_e32 v0, v12, v0
	v_exp_f32_e32 v57, v57
	v_add_f32_e32 v0, v64, v0
	v_exp_f32_e32 v59, v59
	v_add_f32_e32 v0, v50, v0
	v_exp_f32_e32 v61, v61
	v_add_f32_e32 v0, v52, v0
	v_exp_f32_e32 v66, v66
	v_add_f32_e32 v0, v55, v0
	v_exp_f32_e32 v67, v67
	v_add_f32_e32 v0, v57, v0
	v_exp_f32_e32 v68, v68
	v_add_f32_e32 v0, v59, v0
	v_add_f32_e32 v0, v61, v0
	v_exp_f32_e32 v70, v3
	v_add_f32_e32 v0, v66, v0
	v_exp_f32_e32 v71, v5
	v_add_f32_e32 v0, v67, v0
	v_exp_f32_e32 v72, v7
	v_add_f32_e32 v0, v68, v0
	v_exp_f32_e32 v73, v9
	v_add_f32_e32 v0, v69, v0
	v_exp_f32_e32 v74, v11
	v_add_f32_e32 v0, v70, v0
	v_exp_f32_e32 v13, v13
	v_add_f32_e32 v0, v71, v0
	v_exp_f32_e32 v15, v15
	v_add_f32_e32 v0, v72, v0
	v_exp_f32_e32 v51, v51
	v_add_f32_e32 v0, v73, v0
	v_exp_f32_e32 v53, v53
	v_add_f32_e32 v0, v74, v0
	v_exp_f32_e32 v56, v56
	v_add_f32_e32 v0, v13, v0
	v_exp_f32_e32 v58, v58
	v_add_f32_e32 v0, v15, v0
	v_exp_f32_e32 v60, v60
	v_add_f32_e32 v0, v51, v0
	v_exp_f32_e32 v62, v62
	v_add_f32_e32 v0, v53, v0
	v_exp_f32_e32 v63, v63
	v_add_f32_e32 v0, v56, v0
	v_mul_f32_e32 v54, 0x3fb8aa3b, v54
	v_exp_f32_e32 v65, v65
	v_add_f32_e32 v0, v58, v0
	v_exp_f32_e32 v54, v54
	v_add_f32_e32 v0, v60, v0
	v_add_f32_e32 v0, v62, v0
	v_add_f32_e32 v0, v63, v0
	v_add_f32_e32 v0, v65, v0
	v_cndmask_b32_e64 v54, v54, 1.0, vcc
	v_mov_b32_e32 v14, v0
	v_cvt_pk_bf16_f32 v2, v2, v4
	v_cvt_pk_bf16_f32 v3, v6, v8
	v_cvt_pk_bf16_f32 v4, v10, v12
	v_cvt_pk_bf16_f32 v5, v64, v50
	v_cvt_pk_bf16_f32 v6, v52, v55
	v_cvt_pk_bf16_f32 v7, v57, v59
	v_cvt_pk_bf16_f32 v8, v61, v66
	v_cvt_pk_bf16_f32 v9, v67, v68
	v_cvt_pk_bf16_f32 v10, v69, v70
	v_cvt_pk_bf16_f32 v11, v71, v72
	v_cvt_pk_bf16_f32 v12, v73, v74
	v_cvt_pk_bf16_f32 v13, v13, v15
	v_cvt_pk_bf16_f32 v50, v51, v53
	v_cvt_pk_bf16_f32 v51, v56, v58
	v_cvt_pk_bf16_f32 v52, v60, v62
	v_cvt_pk_bf16_f32 v53, v63, v65
	v_permlane32_swap_b32_e32 v0, v14
	v_permlane32_swap_b32_e32 v2, v4
	v_permlane32_swap_b32_e32 v3, v5
	v_permlane32_swap_b32_e32 v6, v8
	v_permlane32_swap_b32_e32 v7, v9
	v_permlane32_swap_b32_e32 v10, v12
	v_permlane32_swap_b32_e32 v11, v13
	v_permlane32_swap_b32_e32 v50, v52
	v_permlane32_swap_b32_e32 v51, v53
	v_cmp_gt_f32_e32 vcc, 1.0, v54
	s_cbranch_vccz .LBB0_457
	s_and_saveexec_b64 vcc, s[38:39]
	ds_write_b32 v113, v54 offset:59008
	s_or_b64 exec, exec, vcc
	s_waitcnt lgkmcnt(0)
	ds_read_b128 v[56:59], v110 offset:59104
	ds_read_b128 v[60:63], v110 offset:59072
	ds_read_b128 v[64:67], v110 offset:59040
	ds_read_b128 v[68:71], v110 offset:59008
	s_waitcnt lgkmcnt(3)
	v_pk_mul_f32 v[46:47], v[46:47], v[58:59]
	s_waitcnt lgkmcnt(2)
	v_pk_mul_f32 v[42:43], v[42:43], v[62:63]
	s_waitcnt lgkmcnt(1)
	v_pk_mul_f32 v[38:39], v[38:39], v[66:67]
	s_waitcnt lgkmcnt(0)
	v_pk_mul_f32 v[34:35], v[34:35], v[70:71]
	v_pk_mul_f32 v[44:45], v[44:45], v[56:57]
	v_pk_mul_f32 v[40:41], v[40:41], v[60:61]
	v_pk_mul_f32 v[36:37], v[36:37], v[64:65]
	v_pk_mul_f32 v[32:33], v[32:33], v[68:69]
	v_pk_mul_f32 v[30:31], v[30:31], v[58:59]
	v_pk_mul_f32 v[26:27], v[26:27], v[62:63]
	v_pk_mul_f32 v[22:23], v[22:23], v[66:67]
	v_pk_mul_f32 v[18:19], v[18:19], v[70:71]
	v_pk_mul_f32 v[28:29], v[28:29], v[56:57]
	v_pk_mul_f32 v[24:25], v[24:25], v[60:61]
	v_pk_mul_f32 v[20:21], v[20:21], v[64:65]
	v_pk_mul_f32 v[16:17], v[16:17], v[68:69]
